# sample-path K-score gather loop software-pipelined (21 loads in flight instead of 1); arithmetic unchanged
# speedup vs baseline: 1.0230x; 1.0230x over previous
.LBB0_310:
	s_mov_b64 s[98:99], exec
	v_add_u32_e32 v174, 0xffffff80, v9
	v_cmp_lt_u32_e32 vcc, s15, v174
	s_nop 1
	v_cndmask_b32_e64 v12, 0, 1, vcc
	v_cmp_gt_u32_e32 vcc, s16, v174
	s_nop 1
	v_cndmask_b32_e32 v12, 2, v12, vcc
	v_mul_i32_i24_e32 v13, 0xffffff7f, v12
	v_lshlrev_b32_e32 v12, 1, v12
	v_add_lshl_u32 v174, v174, v13, v12
	v_sub_u32_e32 v12, v219, v174
	v_add_u32_e32 v14, 0xfffff800, v12
	v_ashrrev_i32_e32 v13, 31, v12
	v_cmp_gt_i32_e32 vcc, s33, v12
	s_nop 1
	v_cndmask_b32_e32 v13, 0, v13, vcc
	v_cndmask_b32_e32 v12, v14, v12, vcc
	v_cndmask_b32_e32 v15, v7, v5, vcc
	v_cndmask_b32_e32 v14, v6, v4, vcc
	v_lshlrev_b64 v[12:13], 11, v[12:13]
	v_lshl_add_u64 v[12:13], v[14:15], 0, v[12:13]
	global_load_dwordx4 v[16:19], v[12:13], off
	v_add_u32_e32 v175, 0xffffff84, v9
	v_cmp_lt_u32_e32 vcc, s15, v175
	s_nop 1
	v_cndmask_b32_e64 v12, 0, 1, vcc
	v_cmp_gt_u32_e32 vcc, s16, v175
	s_nop 1
	v_cndmask_b32_e32 v12, 2, v12, vcc
	v_mul_i32_i24_e32 v13, 0xffffff7f, v12
	v_lshlrev_b32_e32 v12, 1, v12
	v_add_lshl_u32 v175, v175, v13, v12
	v_sub_u32_e32 v12, v219, v175
	v_add_u32_e32 v14, 0xfffff800, v12
	v_ashrrev_i32_e32 v13, 31, v12
	v_cmp_gt_i32_e32 vcc, s33, v12
	s_nop 1
	v_cndmask_b32_e32 v13, 0, v13, vcc
	v_cndmask_b32_e32 v12, v14, v12, vcc
	v_cndmask_b32_e32 v15, v7, v5, vcc
	v_cndmask_b32_e32 v14, v6, v4, vcc
	v_lshlrev_b64 v[12:13], 11, v[12:13]
	v_lshl_add_u64 v[12:13], v[14:15], 0, v[12:13]
	global_load_dwordx4 v[20:23], v[12:13], off
	v_add_u32_e32 v176, 0xffffff88, v9
	v_cmp_lt_u32_e32 vcc, s15, v176
	s_nop 1
	v_cndmask_b32_e64 v12, 0, 1, vcc
	v_cmp_gt_u32_e32 vcc, s16, v176
	s_nop 1
	v_cndmask_b32_e32 v12, 2, v12, vcc
	v_mul_i32_i24_e32 v13, 0xffffff7f, v12
	v_lshlrev_b32_e32 v12, 1, v12
	v_add_lshl_u32 v176, v176, v13, v12
	v_sub_u32_e32 v12, v219, v176
	v_add_u32_e32 v14, 0xfffff800, v12
	v_ashrrev_i32_e32 v13, 31, v12
	v_cmp_gt_i32_e32 vcc, s33, v12
	s_nop 1
	v_cndmask_b32_e32 v13, 0, v13, vcc
	v_cndmask_b32_e32 v12, v14, v12, vcc
	v_cndmask_b32_e32 v15, v7, v5, vcc
	v_cndmask_b32_e32 v14, v6, v4, vcc
	v_lshlrev_b64 v[12:13], 11, v[12:13]
	v_lshl_add_u64 v[12:13], v[14:15], 0, v[12:13]
	global_load_dwordx4 v[24:27], v[12:13], off
	v_add_u32_e32 v177, 0xffffff8c, v9
	v_cmp_lt_u32_e32 vcc, s15, v177
	s_nop 1
	v_cndmask_b32_e64 v12, 0, 1, vcc
	v_cmp_gt_u32_e32 vcc, s16, v177
	s_nop 1
	v_cndmask_b32_e32 v12, 2, v12, vcc
	v_mul_i32_i24_e32 v13, 0xffffff7f, v12
	v_lshlrev_b32_e32 v12, 1, v12
	v_add_lshl_u32 v177, v177, v13, v12
	v_sub_u32_e32 v12, v219, v177
	v_add_u32_e32 v14, 0xfffff800, v12
	v_ashrrev_i32_e32 v13, 31, v12
	v_cmp_gt_i32_e32 vcc, s33, v12
	s_nop 1
	v_cndmask_b32_e32 v13, 0, v13, vcc
	v_cndmask_b32_e32 v12, v14, v12, vcc
	v_cndmask_b32_e32 v15, v7, v5, vcc
	v_cndmask_b32_e32 v14, v6, v4, vcc
	v_lshlrev_b64 v[12:13], 11, v[12:13]
	v_lshl_add_u64 v[12:13], v[14:15], 0, v[12:13]
	global_load_dwordx4 v[28:31], v[12:13], off
	v_add_u32_e32 v178, 0xffffff90, v9
	v_cmp_lt_u32_e32 vcc, s15, v178
	s_nop 1
	v_cndmask_b32_e64 v12, 0, 1, vcc
	v_cmp_gt_u32_e32 vcc, s16, v178
	s_nop 1
	v_cndmask_b32_e32 v12, 2, v12, vcc
	v_mul_i32_i24_e32 v13, 0xffffff7f, v12
	v_lshlrev_b32_e32 v12, 1, v12
	v_add_lshl_u32 v178, v178, v13, v12
	v_sub_u32_e32 v12, v219, v178
	v_add_u32_e32 v14, 0xfffff800, v12
	v_ashrrev_i32_e32 v13, 31, v12
	v_cmp_gt_i32_e32 vcc, s33, v12
	s_nop 1
	v_cndmask_b32_e32 v13, 0, v13, vcc
	v_cndmask_b32_e32 v12, v14, v12, vcc
	v_cndmask_b32_e32 v15, v7, v5, vcc
	v_cndmask_b32_e32 v14, v6, v4, vcc
	v_lshlrev_b64 v[12:13], 11, v[12:13]
	v_lshl_add_u64 v[12:13], v[14:15], 0, v[12:13]
	global_load_dwordx4 v[32:35], v[12:13], off
	v_add_u32_e32 v179, 0xffffff94, v9
	v_cmp_lt_u32_e32 vcc, s15, v179
	s_nop 1
	v_cndmask_b32_e64 v12, 0, 1, vcc
	v_cmp_gt_u32_e32 vcc, s16, v179
	s_nop 1
	v_cndmask_b32_e32 v12, 2, v12, vcc
	v_mul_i32_i24_e32 v13, 0xffffff7f, v12
	v_lshlrev_b32_e32 v12, 1, v12
	v_add_lshl_u32 v179, v179, v13, v12
	v_sub_u32_e32 v12, v219, v179
	v_add_u32_e32 v14, 0xfffff800, v12
	v_ashrrev_i32_e32 v13, 31, v12
	v_cmp_gt_i32_e32 vcc, s33, v12
	s_nop 1
	v_cndmask_b32_e32 v13, 0, v13, vcc
	v_cndmask_b32_e32 v12, v14, v12, vcc
	v_cndmask_b32_e32 v15, v7, v5, vcc
	v_cndmask_b32_e32 v14, v6, v4, vcc
	v_lshlrev_b64 v[12:13], 11, v[12:13]
	v_lshl_add_u64 v[12:13], v[14:15], 0, v[12:13]
	global_load_dwordx4 v[36:39], v[12:13], off
	v_add_u32_e32 v180, 0xffffff98, v9
	v_cmp_lt_u32_e32 vcc, s15, v180
	s_nop 1
	v_cndmask_b32_e64 v12, 0, 1, vcc
	v_cmp_gt_u32_e32 vcc, s16, v180
	s_nop 1
	v_cndmask_b32_e32 v12, 2, v12, vcc
	v_mul_i32_i24_e32 v13, 0xffffff7f, v12
	v_lshlrev_b32_e32 v12, 1, v12
	v_add_lshl_u32 v180, v180, v13, v12
	v_sub_u32_e32 v12, v219, v180
	v_add_u32_e32 v14, 0xfffff800, v12
	v_ashrrev_i32_e32 v13, 31, v12
	v_cmp_gt_i32_e32 vcc, s33, v12
	s_nop 1
	v_cndmask_b32_e32 v13, 0, v13, vcc
	v_cndmask_b32_e32 v12, v14, v12, vcc
	v_cndmask_b32_e32 v15, v7, v5, vcc
	v_cndmask_b32_e32 v14, v6, v4, vcc
	v_lshlrev_b64 v[12:13], 11, v[12:13]
	v_lshl_add_u64 v[12:13], v[14:15], 0, v[12:13]
	global_load_dwordx4 v[40:43], v[12:13], off
	v_add_u32_e32 v181, 0xffffff9c, v9
	v_cmp_lt_u32_e32 vcc, s15, v181
	s_nop 1
	v_cndmask_b32_e64 v12, 0, 1, vcc
	v_cmp_gt_u32_e32 vcc, s16, v181
	s_nop 1
	v_cndmask_b32_e32 v12, 2, v12, vcc
	v_mul_i32_i24_e32 v13, 0xffffff7f, v12
	v_lshlrev_b32_e32 v12, 1, v12
	v_add_lshl_u32 v181, v181, v13, v12
	v_sub_u32_e32 v12, v219, v181
	v_add_u32_e32 v14, 0xfffff800, v12
	v_ashrrev_i32_e32 v13, 31, v12
	v_cmp_gt_i32_e32 vcc, s33, v12
	s_nop 1
	v_cndmask_b32_e32 v13, 0, v13, vcc
	v_cndmask_b32_e32 v12, v14, v12, vcc
	v_cndmask_b32_e32 v15, v7, v5, vcc
	v_cndmask_b32_e32 v14, v6, v4, vcc
	v_lshlrev_b64 v[12:13], 11, v[12:13]
	v_lshl_add_u64 v[12:13], v[14:15], 0, v[12:13]
	global_load_dwordx4 v[44:47], v[12:13], off
	v_add_u32_e32 v182, 0xffffffa0, v9
	v_cmp_lt_u32_e32 vcc, s15, v182
	s_nop 1
	v_cndmask_b32_e64 v12, 0, 1, vcc
	v_cmp_gt_u32_e32 vcc, s16, v182
	s_nop 1
	v_cndmask_b32_e32 v12, 2, v12, vcc
	v_mul_i32_i24_e32 v13, 0xffffff7f, v12
	v_lshlrev_b32_e32 v12, 1, v12
	v_add_lshl_u32 v182, v182, v13, v12
	v_sub_u32_e32 v12, v219, v182
	v_add_u32_e32 v14, 0xfffff800, v12
	v_ashrrev_i32_e32 v13, 31, v12
	v_cmp_gt_i32_e32 vcc, s33, v12
	s_nop 1
	v_cndmask_b32_e32 v13, 0, v13, vcc
	v_cndmask_b32_e32 v12, v14, v12, vcc
	v_cndmask_b32_e32 v15, v7, v5, vcc
	v_cndmask_b32_e32 v14, v6, v4, vcc
	v_lshlrev_b64 v[12:13], 11, v[12:13]
	v_lshl_add_u64 v[12:13], v[14:15], 0, v[12:13]
	global_load_dwordx4 v[48:51], v[12:13], off
	v_add_u32_e32 v183, 0xffffffa4, v9
	v_cmp_lt_u32_e32 vcc, s15, v183
	s_nop 1
	v_cndmask_b32_e64 v12, 0, 1, vcc
	v_cmp_gt_u32_e32 vcc, s16, v183
	s_nop 1
	v_cndmask_b32_e32 v12, 2, v12, vcc
	v_mul_i32_i24_e32 v13, 0xffffff7f, v12
	v_lshlrev_b32_e32 v12, 1, v12
	v_add_lshl_u32 v183, v183, v13, v12
	v_sub_u32_e32 v12, v219, v183
	v_add_u32_e32 v14, 0xfffff800, v12
	v_ashrrev_i32_e32 v13, 31, v12
	v_cmp_gt_i32_e32 vcc, s33, v12
	s_nop 1
	v_cndmask_b32_e32 v13, 0, v13, vcc
	v_cndmask_b32_e32 v12, v14, v12, vcc
	v_cndmask_b32_e32 v15, v7, v5, vcc
	v_cndmask_b32_e32 v14, v6, v4, vcc
	v_lshlrev_b64 v[12:13], 11, v[12:13]
	v_lshl_add_u64 v[12:13], v[14:15], 0, v[12:13]
	global_load_dwordx4 v[52:55], v[12:13], off
	v_add_u32_e32 v184, 0xffffffa8, v9
	v_cmp_lt_u32_e32 vcc, s15, v184
	s_nop 1
	v_cndmask_b32_e64 v12, 0, 1, vcc
	v_cmp_gt_u32_e32 vcc, s16, v184
	s_nop 1
	v_cndmask_b32_e32 v12, 2, v12, vcc
	v_mul_i32_i24_e32 v13, 0xffffff7f, v12
	v_lshlrev_b32_e32 v12, 1, v12
	v_add_lshl_u32 v184, v184, v13, v12
	v_sub_u32_e32 v12, v219, v184
	v_add_u32_e32 v14, 0xfffff800, v12
	v_ashrrev_i32_e32 v13, 31, v12
	v_cmp_gt_i32_e32 vcc, s33, v12
	s_nop 1
	v_cndmask_b32_e32 v13, 0, v13, vcc
	v_cndmask_b32_e32 v12, v14, v12, vcc
	v_cndmask_b32_e32 v15, v7, v5, vcc
	v_cndmask_b32_e32 v14, v6, v4, vcc
	v_lshlrev_b64 v[12:13], 11, v[12:13]
	v_lshl_add_u64 v[12:13], v[14:15], 0, v[12:13]
	global_load_dwordx4 v[56:59], v[12:13], off
	v_add_u32_e32 v185, 0xffffffac, v9
	v_cmp_lt_u32_e32 vcc, s15, v185
	s_nop 1
	v_cndmask_b32_e64 v12, 0, 1, vcc
	v_cmp_gt_u32_e32 vcc, s16, v185
	s_nop 1
	v_cndmask_b32_e32 v12, 2, v12, vcc
	v_mul_i32_i24_e32 v13, 0xffffff7f, v12
	v_lshlrev_b32_e32 v12, 1, v12
	v_add_lshl_u32 v185, v185, v13, v12
	v_sub_u32_e32 v12, v219, v185
	v_add_u32_e32 v14, 0xfffff800, v12
	v_ashrrev_i32_e32 v13, 31, v12
	v_cmp_gt_i32_e32 vcc, s33, v12
	s_nop 1
	v_cndmask_b32_e32 v13, 0, v13, vcc
	v_cndmask_b32_e32 v12, v14, v12, vcc
	v_cndmask_b32_e32 v15, v7, v5, vcc
	v_cndmask_b32_e32 v14, v6, v4, vcc
	v_lshlrev_b64 v[12:13], 11, v[12:13]
	v_lshl_add_u64 v[12:13], v[14:15], 0, v[12:13]
	global_load_dwordx4 v[60:63], v[12:13], off
	v_add_u32_e32 v186, 0xffffffb0, v9
	v_cmp_lt_u32_e32 vcc, s15, v186
	s_nop 1
	v_cndmask_b32_e64 v12, 0, 1, vcc
	v_cmp_gt_u32_e32 vcc, s16, v186
	s_nop 1
	v_cndmask_b32_e32 v12, 2, v12, vcc
	v_mul_i32_i24_e32 v13, 0xffffff7f, v12
	v_lshlrev_b32_e32 v12, 1, v12
	v_add_lshl_u32 v186, v186, v13, v12
	v_sub_u32_e32 v12, v219, v186
	v_add_u32_e32 v14, 0xfffff800, v12
	v_ashrrev_i32_e32 v13, 31, v12
	v_cmp_gt_i32_e32 vcc, s33, v12
	s_nop 1
	v_cndmask_b32_e32 v13, 0, v13, vcc
	v_cndmask_b32_e32 v12, v14, v12, vcc
	v_cndmask_b32_e32 v15, v7, v5, vcc
	v_cndmask_b32_e32 v14, v6, v4, vcc
	v_lshlrev_b64 v[12:13], 11, v[12:13]
	v_lshl_add_u64 v[12:13], v[14:15], 0, v[12:13]
	global_load_dwordx4 v[64:67], v[12:13], off
	v_add_u32_e32 v187, 0xffffffb4, v9
	v_cmp_lt_u32_e32 vcc, s15, v187
	s_nop 1
	v_cndmask_b32_e64 v12, 0, 1, vcc
	v_cmp_gt_u32_e32 vcc, s16, v187
	s_nop 1
	v_cndmask_b32_e32 v12, 2, v12, vcc
	v_mul_i32_i24_e32 v13, 0xffffff7f, v12
	v_lshlrev_b32_e32 v12, 1, v12
	v_add_lshl_u32 v187, v187, v13, v12
	v_sub_u32_e32 v12, v219, v187
	v_add_u32_e32 v14, 0xfffff800, v12
	v_ashrrev_i32_e32 v13, 31, v12
	v_cmp_gt_i32_e32 vcc, s33, v12
	s_nop 1
	v_cndmask_b32_e32 v13, 0, v13, vcc
	v_cndmask_b32_e32 v12, v14, v12, vcc
	v_cndmask_b32_e32 v15, v7, v5, vcc
	v_cndmask_b32_e32 v14, v6, v4, vcc
	v_lshlrev_b64 v[12:13], 11, v[12:13]
	v_lshl_add_u64 v[12:13], v[14:15], 0, v[12:13]
	global_load_dwordx4 v[68:71], v[12:13], off
	v_add_u32_e32 v188, 0xffffffb8, v9
	v_cmp_lt_u32_e32 vcc, s15, v188
	s_nop 1
	v_cndmask_b32_e64 v12, 0, 1, vcc
	v_cmp_gt_u32_e32 vcc, s16, v188
	s_nop 1
	v_cndmask_b32_e32 v12, 2, v12, vcc
	v_mul_i32_i24_e32 v13, 0xffffff7f, v12
	v_lshlrev_b32_e32 v12, 1, v12
	v_add_lshl_u32 v188, v188, v13, v12
	v_sub_u32_e32 v12, v219, v188
	v_add_u32_e32 v14, 0xfffff800, v12
	v_ashrrev_i32_e32 v13, 31, v12
	v_cmp_gt_i32_e32 vcc, s33, v12
	s_nop 1
	v_cndmask_b32_e32 v13, 0, v13, vcc
	v_cndmask_b32_e32 v12, v14, v12, vcc
	v_cndmask_b32_e32 v15, v7, v5, vcc
	v_cndmask_b32_e32 v14, v6, v4, vcc
	v_lshlrev_b64 v[12:13], 11, v[12:13]
	v_lshl_add_u64 v[12:13], v[14:15], 0, v[12:13]
	global_load_dwordx4 v[72:75], v[12:13], off
	v_add_u32_e32 v194, 0xffffffbc, v9
	v_cmp_lt_u32_e32 vcc, s15, v194
	s_nop 1
	v_cndmask_b32_e64 v12, 0, 1, vcc
	v_cmp_gt_u32_e32 vcc, s16, v194
	s_nop 1
	v_cndmask_b32_e32 v12, 2, v12, vcc
	v_mul_i32_i24_e32 v13, 0xffffff7f, v12
	v_lshlrev_b32_e32 v12, 1, v12
	v_add_lshl_u32 v194, v194, v13, v12
	v_sub_u32_e32 v12, v219, v194
	v_add_u32_e32 v14, 0xfffff800, v12
	v_ashrrev_i32_e32 v13, 31, v12
	v_cmp_gt_i32_e32 vcc, s33, v12
	s_nop 1
	v_cndmask_b32_e32 v13, 0, v13, vcc
	v_cndmask_b32_e32 v12, v14, v12, vcc
	v_cndmask_b32_e32 v15, v7, v5, vcc
	v_cndmask_b32_e32 v14, v6, v4, vcc
	v_lshlrev_b64 v[12:13], 11, v[12:13]
	v_lshl_add_u64 v[12:13], v[14:15], 0, v[12:13]
	global_load_dwordx4 v[76:79], v[12:13], off
	v_add_u32_e32 v195, 0xffffffc0, v9
	v_cmp_lt_u32_e32 vcc, s15, v195
	s_nop 1
	v_cndmask_b32_e64 v12, 0, 1, vcc
	v_cmp_gt_u32_e32 vcc, s16, v195
	s_nop 1
	v_cndmask_b32_e32 v12, 2, v12, vcc
	v_mul_i32_i24_e32 v13, 0xffffff7f, v12
	v_lshlrev_b32_e32 v12, 1, v12
	v_add_lshl_u32 v195, v195, v13, v12
	v_sub_u32_e32 v12, v219, v195
	v_add_u32_e32 v14, 0xfffff800, v12
	v_ashrrev_i32_e32 v13, 31, v12
	v_cmp_gt_i32_e32 vcc, s33, v12
	s_nop 1
	v_cndmask_b32_e32 v13, 0, v13, vcc
	v_cndmask_b32_e32 v12, v14, v12, vcc
	v_cndmask_b32_e32 v15, v7, v5, vcc
	v_cndmask_b32_e32 v14, v6, v4, vcc
	v_lshlrev_b64 v[12:13], 11, v[12:13]
	v_lshl_add_u64 v[12:13], v[14:15], 0, v[12:13]
	global_load_dwordx4 v[80:83], v[12:13], off
	v_add_u32_e32 v196, 0xffffffc4, v9
	v_cmp_lt_u32_e32 vcc, s15, v196
	s_nop 1
	v_cndmask_b32_e64 v12, 0, 1, vcc
	v_cmp_gt_u32_e32 vcc, s16, v196
	s_nop 1
	v_cndmask_b32_e32 v12, 2, v12, vcc
	v_mul_i32_i24_e32 v13, 0xffffff7f, v12
	v_lshlrev_b32_e32 v12, 1, v12
	v_add_lshl_u32 v196, v196, v13, v12
	v_sub_u32_e32 v12, v219, v196
	v_add_u32_e32 v14, 0xfffff800, v12
	v_ashrrev_i32_e32 v13, 31, v12
	v_cmp_gt_i32_e32 vcc, s33, v12
	s_nop 1
	v_cndmask_b32_e32 v13, 0, v13, vcc
	v_cndmask_b32_e32 v12, v14, v12, vcc
	v_cndmask_b32_e32 v15, v7, v5, vcc
	v_cndmask_b32_e32 v14, v6, v4, vcc
	v_lshlrev_b64 v[12:13], 11, v[12:13]
	v_lshl_add_u64 v[12:13], v[14:15], 0, v[12:13]
	global_load_dwordx4 v[84:87], v[12:13], off
	v_add_u32_e32 v197, 0xffffffc8, v9
	v_cmp_lt_u32_e32 vcc, s15, v197
	s_nop 1
	v_cndmask_b32_e64 v12, 0, 1, vcc
	v_cmp_gt_u32_e32 vcc, s16, v197
	s_nop 1
	v_cndmask_b32_e32 v12, 2, v12, vcc
	v_mul_i32_i24_e32 v13, 0xffffff7f, v12
	v_lshlrev_b32_e32 v12, 1, v12
	v_add_lshl_u32 v197, v197, v13, v12
	v_sub_u32_e32 v12, v219, v197
	v_add_u32_e32 v14, 0xfffff800, v12
	v_ashrrev_i32_e32 v13, 31, v12
	v_cmp_gt_i32_e32 vcc, s33, v12
	s_nop 1
	v_cndmask_b32_e32 v13, 0, v13, vcc
	v_cndmask_b32_e32 v12, v14, v12, vcc
	v_cndmask_b32_e32 v15, v7, v5, vcc
	v_cndmask_b32_e32 v14, v6, v4, vcc
	v_lshlrev_b64 v[12:13], 11, v[12:13]
	v_lshl_add_u64 v[12:13], v[14:15], 0, v[12:13]
	global_load_dwordx4 v[88:91], v[12:13], off
	v_add_u32_e32 v198, 0xffffffcc, v9
	v_cmp_lt_u32_e32 vcc, s15, v198
	s_nop 1
	v_cndmask_b32_e64 v12, 0, 1, vcc
	v_cmp_gt_u32_e32 vcc, s16, v198
	s_nop 1
	v_cndmask_b32_e32 v12, 2, v12, vcc
	v_mul_i32_i24_e32 v13, 0xffffff7f, v12
	v_lshlrev_b32_e32 v12, 1, v12
	v_add_lshl_u32 v198, v198, v13, v12
	v_sub_u32_e32 v12, v219, v198
	v_add_u32_e32 v14, 0xfffff800, v12
	v_ashrrev_i32_e32 v13, 31, v12
	v_cmp_gt_i32_e32 vcc, s33, v12
	s_nop 1
	v_cndmask_b32_e32 v13, 0, v13, vcc
	v_cndmask_b32_e32 v12, v14, v12, vcc
	v_cndmask_b32_e32 v15, v7, v5, vcc
	v_cndmask_b32_e32 v14, v6, v4, vcc
	v_lshlrev_b64 v[12:13], 11, v[12:13]
	v_lshl_add_u64 v[12:13], v[14:15], 0, v[12:13]
	global_load_dwordx4 v[92:95], v[12:13], off
	v_add_u32_e32 v199, 0xffffffd0, v9
	v_cmp_lt_u32_e32 vcc, s15, v199
	s_nop 1
	v_cndmask_b32_e64 v12, 0, 1, vcc
	v_cmp_gt_u32_e32 vcc, s16, v199
	s_nop 1
	v_cndmask_b32_e32 v12, 2, v12, vcc
	v_mul_i32_i24_e32 v13, 0xffffff7f, v12
	v_lshlrev_b32_e32 v12, 1, v12
	v_add_lshl_u32 v199, v199, v13, v12
	v_sub_u32_e32 v12, v219, v199
	v_add_u32_e32 v14, 0xfffff800, v12
	v_ashrrev_i32_e32 v13, 31, v12
	v_cmp_gt_i32_e32 vcc, s33, v12
	s_nop 1
	v_cndmask_b32_e32 v13, 0, v13, vcc
	v_cndmask_b32_e32 v12, v14, v12, vcc
	v_cndmask_b32_e32 v15, v7, v5, vcc
	v_cndmask_b32_e32 v14, v6, v4, vcc
	v_lshlrev_b64 v[12:13], 11, v[12:13]
	v_lshl_add_u64 v[12:13], v[14:15], 0, v[12:13]
	global_load_dwordx4 v[96:99], v[12:13], off
	s_waitcnt lgkmcnt(0)
	s_waitcnt vmcnt(18)
	v_mul_f32_e32 v17, v1, v17
	v_mul_f32_e32 v21, v1, v21
	v_mul_f32_e32 v25, v1, v25
	v_mul_f32_e32 v19, v3, v19
	v_mul_f32_e32 v23, v3, v23
	v_mul_f32_e32 v27, v3, v27
	v_fmac_f32_e32 v17, v0, v16
	v_fmac_f32_e32 v21, v0, v20
	v_fmac_f32_e32 v25, v0, v24
	v_fmac_f32_e32 v19, v2, v18
	v_fmac_f32_e32 v23, v2, v22
	v_fmac_f32_e32 v27, v2, v26
	v_add_f32_e32 v16, v17, v19
	v_add_f32_e32 v20, v21, v23
	v_add_f32_e32 v24, v25, v27
	v_mov_b32_e32 v18, 0
	v_mov_b32_e32 v22, 0
	v_mov_b32_e32 v26, 0
	v_add_f32_dpp v16, v16, v16 row_ror:8 row_mask:0xf bank_mask:0xf bound_ctrl:1
	v_add_f32_dpp v20, v20, v20 row_ror:8 row_mask:0xf bank_mask:0xf bound_ctrl:1
	v_add_f32_dpp v24, v24, v24 row_ror:8 row_mask:0xf bank_mask:0xf bound_ctrl:1
	v_add_f32_dpp v16, v16, v16 row_ror:4 row_mask:0xf bank_mask:0xf bound_ctrl:1
	v_add_f32_dpp v20, v20, v20 row_ror:4 row_mask:0xf bank_mask:0xf bound_ctrl:1
	v_add_f32_dpp v24, v24, v24 row_ror:4 row_mask:0xf bank_mask:0xf bound_ctrl:1
	v_add_f32_dpp v16, v16, v16 row_ror:2 row_mask:0xf bank_mask:0xf bound_ctrl:1
	v_add_f32_dpp v20, v20, v20 row_ror:2 row_mask:0xf bank_mask:0xf bound_ctrl:1
	v_add_f32_dpp v24, v24, v24 row_ror:2 row_mask:0xf bank_mask:0xf bound_ctrl:1
	v_mov_b32_dpp v18, v16 row_ror:1 row_mask:0xf bank_mask:0xf
	v_mov_b32_dpp v22, v20 row_ror:1 row_mask:0xf bank_mask:0xf
	v_mov_b32_dpp v26, v24 row_ror:1 row_mask:0xf bank_mask:0xf
	v_cvt_f32_i32_e32 v174, v174
	v_cvt_f32_i32_e32 v175, v175
	v_cvt_f32_i32_e32 v176, v176
	v_add_f32_e32 v16, v16, v18
	v_add_f32_e32 v20, v20, v22
	v_add_f32_e32 v24, v24, v26
	v_fma_f32 v174, -v8, v174, v16
	v_fma_f32 v175, -v8, v175, v20
	v_fma_f32 v176, -v8, v176, v24
	v_mul_f32_e32 v174, 0x3fb8aa3b, v174
	v_mul_f32_e32 v175, 0x3fb8aa3b, v175
	v_mul_f32_e32 v176, 0x3fb8aa3b, v176
	s_and_b64 exec, s[98:99], s[10:11]
	ds_write_b32 v10, v174
	ds_write_b32 v10, v175 offset:16
	ds_write_b32 v10, v176 offset:32
	s_mov_b64 exec, s[98:99]
	v_add_u32_e32 v200, 0xffffffd4, v9
	v_cmp_lt_u32_e32 vcc, s15, v200
	s_nop 1
	v_cndmask_b32_e64 v12, 0, 1, vcc
	v_cmp_gt_u32_e32 vcc, s16, v200
	s_nop 1
	v_cndmask_b32_e32 v12, 2, v12, vcc
	v_mul_i32_i24_e32 v13, 0xffffff7f, v12
	v_lshlrev_b32_e32 v12, 1, v12
	v_add_lshl_u32 v200, v200, v13, v12
	v_sub_u32_e32 v12, v219, v200
	v_add_u32_e32 v14, 0xfffff800, v12
	v_ashrrev_i32_e32 v13, 31, v12
	v_cmp_gt_i32_e32 vcc, s33, v12
	s_nop 1
	v_cndmask_b32_e32 v13, 0, v13, vcc
	v_cndmask_b32_e32 v12, v14, v12, vcc
	v_cndmask_b32_e32 v15, v7, v5, vcc
	v_cndmask_b32_e32 v14, v6, v4, vcc
	v_lshlrev_b64 v[12:13], 11, v[12:13]
	v_lshl_add_u64 v[12:13], v[14:15], 0, v[12:13]
	global_load_dwordx4 v[16:19], v[12:13], off
	v_add_u32_e32 v201, 0xffffffd8, v9
	v_cmp_lt_u32_e32 vcc, s15, v201
	s_nop 1
	v_cndmask_b32_e64 v12, 0, 1, vcc
	v_cmp_gt_u32_e32 vcc, s16, v201
	s_nop 1
	v_cndmask_b32_e32 v12, 2, v12, vcc
	v_mul_i32_i24_e32 v13, 0xffffff7f, v12
	v_lshlrev_b32_e32 v12, 1, v12
	v_add_lshl_u32 v201, v201, v13, v12
	v_sub_u32_e32 v12, v219, v201
	v_add_u32_e32 v14, 0xfffff800, v12
	v_ashrrev_i32_e32 v13, 31, v12
	v_cmp_gt_i32_e32 vcc, s33, v12
	s_nop 1
	v_cndmask_b32_e32 v13, 0, v13, vcc
	v_cndmask_b32_e32 v12, v14, v12, vcc
	v_cndmask_b32_e32 v15, v7, v5, vcc
	v_cndmask_b32_e32 v14, v6, v4, vcc
	v_lshlrev_b64 v[12:13], 11, v[12:13]
	v_lshl_add_u64 v[12:13], v[14:15], 0, v[12:13]
	global_load_dwordx4 v[20:23], v[12:13], off
	v_add_u32_e32 v202, 0xffffffdc, v9
	v_cmp_lt_u32_e32 vcc, s15, v202
	s_nop 1
	v_cndmask_b32_e64 v12, 0, 1, vcc
	v_cmp_gt_u32_e32 vcc, s16, v202
	s_nop 1
	v_cndmask_b32_e32 v12, 2, v12, vcc
	v_mul_i32_i24_e32 v13, 0xffffff7f, v12
	v_lshlrev_b32_e32 v12, 1, v12
	v_add_lshl_u32 v202, v202, v13, v12
	v_sub_u32_e32 v12, v219, v202
	v_add_u32_e32 v14, 0xfffff800, v12
	v_ashrrev_i32_e32 v13, 31, v12
	v_cmp_gt_i32_e32 vcc, s33, v12
	s_nop 1
	v_cndmask_b32_e32 v13, 0, v13, vcc
	v_cndmask_b32_e32 v12, v14, v12, vcc
	v_cndmask_b32_e32 v15, v7, v5, vcc
	v_cndmask_b32_e32 v14, v6, v4, vcc
	v_lshlrev_b64 v[12:13], 11, v[12:13]
	v_lshl_add_u64 v[12:13], v[14:15], 0, v[12:13]
	global_load_dwordx4 v[24:27], v[12:13], off
	s_waitcnt vmcnt(18)
	v_mul_f32_e32 v29, v1, v29
	v_mul_f32_e32 v33, v1, v33
	v_mul_f32_e32 v37, v1, v37
	v_mul_f32_e32 v31, v3, v31
	v_mul_f32_e32 v35, v3, v35
	v_mul_f32_e32 v39, v3, v39
	v_fmac_f32_e32 v29, v0, v28
	v_fmac_f32_e32 v33, v0, v32
	v_fmac_f32_e32 v37, v0, v36
	v_fmac_f32_e32 v31, v2, v30
	v_fmac_f32_e32 v35, v2, v34
	v_fmac_f32_e32 v39, v2, v38
	v_add_f32_e32 v28, v29, v31
	v_add_f32_e32 v32, v33, v35
	v_add_f32_e32 v36, v37, v39
	v_mov_b32_e32 v30, 0
	v_mov_b32_e32 v34, 0
	v_mov_b32_e32 v38, 0
	v_add_f32_dpp v28, v28, v28 row_ror:8 row_mask:0xf bank_mask:0xf bound_ctrl:1
	v_add_f32_dpp v32, v32, v32 row_ror:8 row_mask:0xf bank_mask:0xf bound_ctrl:1
	v_add_f32_dpp v36, v36, v36 row_ror:8 row_mask:0xf bank_mask:0xf bound_ctrl:1
	v_add_f32_dpp v28, v28, v28 row_ror:4 row_mask:0xf bank_mask:0xf bound_ctrl:1
	v_add_f32_dpp v32, v32, v32 row_ror:4 row_mask:0xf bank_mask:0xf bound_ctrl:1
	v_add_f32_dpp v36, v36, v36 row_ror:4 row_mask:0xf bank_mask:0xf bound_ctrl:1
	v_add_f32_dpp v28, v28, v28 row_ror:2 row_mask:0xf bank_mask:0xf bound_ctrl:1
	v_add_f32_dpp v32, v32, v32 row_ror:2 row_mask:0xf bank_mask:0xf bound_ctrl:1
	v_add_f32_dpp v36, v36, v36 row_ror:2 row_mask:0xf bank_mask:0xf bound_ctrl:1
	v_mov_b32_dpp v30, v28 row_ror:1 row_mask:0xf bank_mask:0xf
	v_mov_b32_dpp v34, v32 row_ror:1 row_mask:0xf bank_mask:0xf
	v_mov_b32_dpp v38, v36 row_ror:1 row_mask:0xf bank_mask:0xf
	v_cvt_f32_i32_e32 v177, v177
	v_cvt_f32_i32_e32 v178, v178
	v_cvt_f32_i32_e32 v179, v179
	v_add_f32_e32 v28, v28, v30
	v_add_f32_e32 v32, v32, v34
	v_add_f32_e32 v36, v36, v38
	v_fma_f32 v177, -v8, v177, v28
	v_fma_f32 v178, -v8, v178, v32
	v_fma_f32 v179, -v8, v179, v36
	v_mul_f32_e32 v177, 0x3fb8aa3b, v177
	v_mul_f32_e32 v178, 0x3fb8aa3b, v178
	v_mul_f32_e32 v179, 0x3fb8aa3b, v179
	s_and_b64 exec, s[98:99], s[10:11]
	ds_write_b32 v10, v177 offset:48
	ds_write_b32 v10, v178 offset:64
	ds_write_b32 v10, v179 offset:80
	s_mov_b64 exec, s[98:99]
	v_add_u32_e32 v203, 0xffffffe0, v9
	v_cmp_lt_u32_e32 vcc, s15, v203
	s_nop 1
	v_cndmask_b32_e64 v12, 0, 1, vcc
	v_cmp_gt_u32_e32 vcc, s16, v203
	s_nop 1
	v_cndmask_b32_e32 v12, 2, v12, vcc
	v_mul_i32_i24_e32 v13, 0xffffff7f, v12
	v_lshlrev_b32_e32 v12, 1, v12
	v_add_lshl_u32 v203, v203, v13, v12
	v_sub_u32_e32 v12, v219, v203
	v_add_u32_e32 v14, 0xfffff800, v12
	v_ashrrev_i32_e32 v13, 31, v12
	v_cmp_gt_i32_e32 vcc, s33, v12
	s_nop 1
	v_cndmask_b32_e32 v13, 0, v13, vcc
	v_cndmask_b32_e32 v12, v14, v12, vcc
	v_cndmask_b32_e32 v15, v7, v5, vcc
	v_cndmask_b32_e32 v14, v6, v4, vcc
	v_lshlrev_b64 v[12:13], 11, v[12:13]
	v_lshl_add_u64 v[12:13], v[14:15], 0, v[12:13]
	global_load_dwordx4 v[28:31], v[12:13], off
	v_add_u32_e32 v204, 0xffffffe4, v9
	v_cmp_lt_u32_e32 vcc, s15, v204
	s_nop 1
	v_cndmask_b32_e64 v12, 0, 1, vcc
	v_cmp_gt_u32_e32 vcc, s16, v204
	s_nop 1
	v_cndmask_b32_e32 v12, 2, v12, vcc
	v_mul_i32_i24_e32 v13, 0xffffff7f, v12
	v_lshlrev_b32_e32 v12, 1, v12
	v_add_lshl_u32 v204, v204, v13, v12
	v_sub_u32_e32 v12, v219, v204
	v_add_u32_e32 v14, 0xfffff800, v12
	v_ashrrev_i32_e32 v13, 31, v12
	v_cmp_gt_i32_e32 vcc, s33, v12
	s_nop 1
	v_cndmask_b32_e32 v13, 0, v13, vcc
	v_cndmask_b32_e32 v12, v14, v12, vcc
	v_cndmask_b32_e32 v15, v7, v5, vcc
	v_cndmask_b32_e32 v14, v6, v4, vcc
	v_lshlrev_b64 v[12:13], 11, v[12:13]
	v_lshl_add_u64 v[12:13], v[14:15], 0, v[12:13]
	global_load_dwordx4 v[32:35], v[12:13], off
	v_add_u32_e32 v205, 0xffffffe8, v9
	v_cmp_lt_u32_e32 vcc, s15, v205
	s_nop 1
	v_cndmask_b32_e64 v12, 0, 1, vcc
	v_cmp_gt_u32_e32 vcc, s16, v205
	s_nop 1
	v_cndmask_b32_e32 v12, 2, v12, vcc
	v_mul_i32_i24_e32 v13, 0xffffff7f, v12
	v_lshlrev_b32_e32 v12, 1, v12
	v_add_lshl_u32 v205, v205, v13, v12
	v_sub_u32_e32 v12, v219, v205
	v_add_u32_e32 v14, 0xfffff800, v12
	v_ashrrev_i32_e32 v13, 31, v12
	v_cmp_gt_i32_e32 vcc, s33, v12
	s_nop 1
	v_cndmask_b32_e32 v13, 0, v13, vcc
	v_cndmask_b32_e32 v12, v14, v12, vcc
	v_cndmask_b32_e32 v15, v7, v5, vcc
	v_cndmask_b32_e32 v14, v6, v4, vcc
	v_lshlrev_b64 v[12:13], 11, v[12:13]
	v_lshl_add_u64 v[12:13], v[14:15], 0, v[12:13]
	global_load_dwordx4 v[36:39], v[12:13], off
	s_waitcnt vmcnt(18)
	v_mul_f32_e32 v41, v1, v41
	v_mul_f32_e32 v45, v1, v45
	v_mul_f32_e32 v49, v1, v49
	v_mul_f32_e32 v43, v3, v43
	v_mul_f32_e32 v47, v3, v47
	v_mul_f32_e32 v51, v3, v51
	v_fmac_f32_e32 v41, v0, v40
	v_fmac_f32_e32 v45, v0, v44
	v_fmac_f32_e32 v49, v0, v48
	v_fmac_f32_e32 v43, v2, v42
	v_fmac_f32_e32 v47, v2, v46
	v_fmac_f32_e32 v51, v2, v50
	v_add_f32_e32 v40, v41, v43
	v_add_f32_e32 v44, v45, v47
	v_add_f32_e32 v48, v49, v51
	v_mov_b32_e32 v42, 0
	v_mov_b32_e32 v46, 0
	v_mov_b32_e32 v50, 0
	v_add_f32_dpp v40, v40, v40 row_ror:8 row_mask:0xf bank_mask:0xf bound_ctrl:1
	v_add_f32_dpp v44, v44, v44 row_ror:8 row_mask:0xf bank_mask:0xf bound_ctrl:1
	v_add_f32_dpp v48, v48, v48 row_ror:8 row_mask:0xf bank_mask:0xf bound_ctrl:1
	v_add_f32_dpp v40, v40, v40 row_ror:4 row_mask:0xf bank_mask:0xf bound_ctrl:1
	v_add_f32_dpp v44, v44, v44 row_ror:4 row_mask:0xf bank_mask:0xf bound_ctrl:1
	v_add_f32_dpp v48, v48, v48 row_ror:4 row_mask:0xf bank_mask:0xf bound_ctrl:1
	v_add_f32_dpp v40, v40, v40 row_ror:2 row_mask:0xf bank_mask:0xf bound_ctrl:1
	v_add_f32_dpp v44, v44, v44 row_ror:2 row_mask:0xf bank_mask:0xf bound_ctrl:1
	v_add_f32_dpp v48, v48, v48 row_ror:2 row_mask:0xf bank_mask:0xf bound_ctrl:1
	v_mov_b32_dpp v42, v40 row_ror:1 row_mask:0xf bank_mask:0xf
	v_mov_b32_dpp v46, v44 row_ror:1 row_mask:0xf bank_mask:0xf
	v_mov_b32_dpp v50, v48 row_ror:1 row_mask:0xf bank_mask:0xf
	v_cvt_f32_i32_e32 v180, v180
	v_cvt_f32_i32_e32 v181, v181
	v_cvt_f32_i32_e32 v182, v182
	v_add_f32_e32 v40, v40, v42
	v_add_f32_e32 v44, v44, v46
	v_add_f32_e32 v48, v48, v50
	v_fma_f32 v180, -v8, v180, v40
	v_fma_f32 v181, -v8, v181, v44
	v_fma_f32 v182, -v8, v182, v48
	v_mul_f32_e32 v180, 0x3fb8aa3b, v180
	v_mul_f32_e32 v181, 0x3fb8aa3b, v181
	v_mul_f32_e32 v182, 0x3fb8aa3b, v182
	s_and_b64 exec, s[98:99], s[10:11]
	ds_write_b32 v10, v180 offset:96
	ds_write_b32 v10, v181 offset:112
	ds_write_b32 v10, v182 offset:128
	s_mov_b64 exec, s[98:99]
	v_add_u32_e32 v206, 0xffffffec, v9
	v_cmp_lt_u32_e32 vcc, s15, v206
	s_nop 1
	v_cndmask_b32_e64 v12, 0, 1, vcc
	v_cmp_gt_u32_e32 vcc, s16, v206
	s_nop 1
	v_cndmask_b32_e32 v12, 2, v12, vcc
	v_mul_i32_i24_e32 v13, 0xffffff7f, v12
	v_lshlrev_b32_e32 v12, 1, v12
	v_add_lshl_u32 v206, v206, v13, v12
	v_sub_u32_e32 v12, v219, v206
	v_add_u32_e32 v14, 0xfffff800, v12
	v_ashrrev_i32_e32 v13, 31, v12
	v_cmp_gt_i32_e32 vcc, s33, v12
	s_nop 1
	v_cndmask_b32_e32 v13, 0, v13, vcc
	v_cndmask_b32_e32 v12, v14, v12, vcc
	v_cndmask_b32_e32 v15, v7, v5, vcc
	v_cndmask_b32_e32 v14, v6, v4, vcc
	v_lshlrev_b64 v[12:13], 11, v[12:13]
	v_lshl_add_u64 v[12:13], v[14:15], 0, v[12:13]
	global_load_dwordx4 v[40:43], v[12:13], off
	v_add_u32_e32 v207, -16, v9
	v_cmp_lt_u32_e32 vcc, s15, v207
	s_nop 1
	v_cndmask_b32_e64 v12, 0, 1, vcc
	v_cmp_gt_u32_e32 vcc, s16, v207
	s_nop 1
	v_cndmask_b32_e32 v12, 2, v12, vcc
	v_mul_i32_i24_e32 v13, 0xffffff7f, v12
	v_lshlrev_b32_e32 v12, 1, v12
	v_add_lshl_u32 v207, v207, v13, v12
	v_sub_u32_e32 v12, v219, v207
	v_add_u32_e32 v14, 0xfffff800, v12
	v_ashrrev_i32_e32 v13, 31, v12
	v_cmp_gt_i32_e32 vcc, s33, v12
	s_nop 1
	v_cndmask_b32_e32 v13, 0, v13, vcc
	v_cndmask_b32_e32 v12, v14, v12, vcc
	v_cndmask_b32_e32 v15, v7, v5, vcc
	v_cndmask_b32_e32 v14, v6, v4, vcc
	v_lshlrev_b64 v[12:13], 11, v[12:13]
	v_lshl_add_u64 v[12:13], v[14:15], 0, v[12:13]
	global_load_dwordx4 v[44:47], v[12:13], off
	v_add_u32_e32 v208, -12, v9
	v_cmp_lt_u32_e32 vcc, s15, v208
	s_nop 1
	v_cndmask_b32_e64 v12, 0, 1, vcc
	v_cmp_gt_u32_e32 vcc, s16, v208
	s_nop 1
	v_cndmask_b32_e32 v12, 2, v12, vcc
	v_mul_i32_i24_e32 v13, 0xffffff7f, v12
	v_lshlrev_b32_e32 v12, 1, v12
	v_add_lshl_u32 v208, v208, v13, v12
	v_sub_u32_e32 v12, v219, v208
	v_add_u32_e32 v14, 0xfffff800, v12
	v_ashrrev_i32_e32 v13, 31, v12
	v_cmp_gt_i32_e32 vcc, s33, v12
	s_nop 1
	v_cndmask_b32_e32 v13, 0, v13, vcc
	v_cndmask_b32_e32 v12, v14, v12, vcc
	v_cndmask_b32_e32 v15, v7, v5, vcc
	v_cndmask_b32_e32 v14, v6, v4, vcc
	v_lshlrev_b64 v[12:13], 11, v[12:13]
	v_lshl_add_u64 v[12:13], v[14:15], 0, v[12:13]
	global_load_dwordx4 v[48:51], v[12:13], off
	s_waitcnt vmcnt(18)
	v_mul_f32_e32 v53, v1, v53
	v_mul_f32_e32 v57, v1, v57
	v_mul_f32_e32 v61, v1, v61
	v_mul_f32_e32 v55, v3, v55
	v_mul_f32_e32 v59, v3, v59
	v_mul_f32_e32 v63, v3, v63
	v_fmac_f32_e32 v53, v0, v52
	v_fmac_f32_e32 v57, v0, v56
	v_fmac_f32_e32 v61, v0, v60
	v_fmac_f32_e32 v55, v2, v54
	v_fmac_f32_e32 v59, v2, v58
	v_fmac_f32_e32 v63, v2, v62
	v_add_f32_e32 v52, v53, v55
	v_add_f32_e32 v56, v57, v59
	v_add_f32_e32 v60, v61, v63
	v_mov_b32_e32 v54, 0
	v_mov_b32_e32 v58, 0
	v_mov_b32_e32 v62, 0
	v_add_f32_dpp v52, v52, v52 row_ror:8 row_mask:0xf bank_mask:0xf bound_ctrl:1
	v_add_f32_dpp v56, v56, v56 row_ror:8 row_mask:0xf bank_mask:0xf bound_ctrl:1
	v_add_f32_dpp v60, v60, v60 row_ror:8 row_mask:0xf bank_mask:0xf bound_ctrl:1
	v_add_f32_dpp v52, v52, v52 row_ror:4 row_mask:0xf bank_mask:0xf bound_ctrl:1
	v_add_f32_dpp v56, v56, v56 row_ror:4 row_mask:0xf bank_mask:0xf bound_ctrl:1
	v_add_f32_dpp v60, v60, v60 row_ror:4 row_mask:0xf bank_mask:0xf bound_ctrl:1
	v_add_f32_dpp v52, v52, v52 row_ror:2 row_mask:0xf bank_mask:0xf bound_ctrl:1
	v_add_f32_dpp v56, v56, v56 row_ror:2 row_mask:0xf bank_mask:0xf bound_ctrl:1
	v_add_f32_dpp v60, v60, v60 row_ror:2 row_mask:0xf bank_mask:0xf bound_ctrl:1
	v_mov_b32_dpp v54, v52 row_ror:1 row_mask:0xf bank_mask:0xf
	v_mov_b32_dpp v58, v56 row_ror:1 row_mask:0xf bank_mask:0xf
	v_mov_b32_dpp v62, v60 row_ror:1 row_mask:0xf bank_mask:0xf
	v_cvt_f32_i32_e32 v183, v183
	v_cvt_f32_i32_e32 v184, v184
	v_cvt_f32_i32_e32 v185, v185
	v_add_f32_e32 v52, v52, v54
	v_add_f32_e32 v56, v56, v58
	v_add_f32_e32 v60, v60, v62
	v_fma_f32 v183, -v8, v183, v52
	v_fma_f32 v184, -v8, v184, v56
	v_fma_f32 v185, -v8, v185, v60
	v_mul_f32_e32 v183, 0x3fb8aa3b, v183
	v_mul_f32_e32 v184, 0x3fb8aa3b, v184
	v_mul_f32_e32 v185, 0x3fb8aa3b, v185
	s_and_b64 exec, s[98:99], s[10:11]
	ds_write_b32 v10, v183 offset:144
	ds_write_b32 v10, v184 offset:160
	ds_write_b32 v10, v185 offset:176
	s_mov_b64 exec, s[98:99]
	v_add_u32_e32 v190, -8, v9
	v_cmp_gt_u32_e32 vcc, s14, v190
	s_nop 1
	v_cndmask_b32_e32 v190, v239, v190, vcc
	v_cmp_lt_u32_e32 vcc, s15, v190
	s_nop 1
	v_cndmask_b32_e64 v12, 0, 1, vcc
	v_cmp_gt_u32_e32 vcc, s16, v190
	s_nop 1
	v_cndmask_b32_e32 v12, 2, v12, vcc
	v_mul_i32_i24_e32 v13, 0xffffff7f, v12
	v_lshlrev_b32_e32 v12, 1, v12
	v_add_lshl_u32 v190, v190, v13, v12
	v_sub_u32_e32 v12, v219, v190
	v_add_u32_e32 v14, 0xfffff800, v12
	v_ashrrev_i32_e32 v13, 31, v12
	v_cmp_gt_i32_e32 vcc, s33, v12
	s_nop 1
	v_cndmask_b32_e32 v13, 0, v13, vcc
	v_cndmask_b32_e32 v12, v14, v12, vcc
	v_cndmask_b32_e32 v15, v7, v5, vcc
	v_cndmask_b32_e32 v14, v6, v4, vcc
	v_lshlrev_b64 v[12:13], 11, v[12:13]
	v_lshl_add_u64 v[12:13], v[14:15], 0, v[12:13]
	global_load_dwordx4 v[52:55], v[12:13], off
	v_add_u32_e32 v191, -4, v9
	v_cmp_gt_u32_e32 vcc, s14, v191
	s_nop 1
	v_cndmask_b32_e32 v191, v239, v191, vcc
	v_cmp_lt_u32_e32 vcc, s15, v191
	s_nop 1
	v_cndmask_b32_e64 v12, 0, 1, vcc
	v_cmp_gt_u32_e32 vcc, s16, v191
	s_nop 1
	v_cndmask_b32_e32 v12, 2, v12, vcc
	v_mul_i32_i24_e32 v13, 0xffffff7f, v12
	v_lshlrev_b32_e32 v12, 1, v12
	v_add_lshl_u32 v191, v191, v13, v12
	v_sub_u32_e32 v12, v219, v191
	v_add_u32_e32 v14, 0xfffff800, v12
	v_ashrrev_i32_e32 v13, 31, v12
	v_cmp_gt_i32_e32 vcc, s33, v12
	s_nop 1
	v_cndmask_b32_e32 v13, 0, v13, vcc
	v_cndmask_b32_e32 v12, v14, v12, vcc
	v_cndmask_b32_e32 v15, v7, v5, vcc
	v_cndmask_b32_e32 v14, v6, v4, vcc
	v_lshlrev_b64 v[12:13], 11, v[12:13]
	v_lshl_add_u64 v[12:13], v[14:15], 0, v[12:13]
	global_load_dwordx4 v[56:59], v[12:13], off
	v_mov_b32_e32 v192, v9
	v_cmp_gt_u32_e32 vcc, s14, v192
	s_nop 1
	v_cndmask_b32_e32 v192, v239, v192, vcc
	v_cmp_lt_u32_e32 vcc, s15, v192
	s_nop 1
	v_cndmask_b32_e64 v12, 0, 1, vcc
	v_cmp_gt_u32_e32 vcc, s16, v192
	s_nop 1
	v_cndmask_b32_e32 v12, 2, v12, vcc
	v_mul_i32_i24_e32 v13, 0xffffff7f, v12
	v_lshlrev_b32_e32 v12, 1, v12
	v_add_lshl_u32 v192, v192, v13, v12
	v_sub_u32_e32 v12, v219, v192
	v_add_u32_e32 v14, 0xfffff800, v12
	v_ashrrev_i32_e32 v13, 31, v12
	v_cmp_gt_i32_e32 vcc, s33, v12
	s_nop 1
	v_cndmask_b32_e32 v13, 0, v13, vcc
	v_cndmask_b32_e32 v12, v14, v12, vcc
	v_cndmask_b32_e32 v15, v7, v5, vcc
	v_cndmask_b32_e32 v14, v6, v4, vcc
	v_lshlrev_b64 v[12:13], 11, v[12:13]
	v_lshl_add_u64 v[12:13], v[14:15], 0, v[12:13]
	global_load_dwordx4 v[60:63], v[12:13], off
	s_waitcnt vmcnt(18)
	v_mul_f32_e32 v65, v1, v65
	v_mul_f32_e32 v69, v1, v69
	v_mul_f32_e32 v73, v1, v73
	v_mul_f32_e32 v67, v3, v67
	v_mul_f32_e32 v71, v3, v71
	v_mul_f32_e32 v75, v3, v75
	v_fmac_f32_e32 v65, v0, v64
	v_fmac_f32_e32 v69, v0, v68
	v_fmac_f32_e32 v73, v0, v72
	v_fmac_f32_e32 v67, v2, v66
	v_fmac_f32_e32 v71, v2, v70
	v_fmac_f32_e32 v75, v2, v74
	v_add_f32_e32 v64, v65, v67
	v_add_f32_e32 v68, v69, v71
	v_add_f32_e32 v72, v73, v75
	v_mov_b32_e32 v66, 0
	v_mov_b32_e32 v70, 0
	v_mov_b32_e32 v74, 0
	v_add_f32_dpp v64, v64, v64 row_ror:8 row_mask:0xf bank_mask:0xf bound_ctrl:1
	v_add_f32_dpp v68, v68, v68 row_ror:8 row_mask:0xf bank_mask:0xf bound_ctrl:1
	v_add_f32_dpp v72, v72, v72 row_ror:8 row_mask:0xf bank_mask:0xf bound_ctrl:1
	v_add_f32_dpp v64, v64, v64 row_ror:4 row_mask:0xf bank_mask:0xf bound_ctrl:1
	v_add_f32_dpp v68, v68, v68 row_ror:4 row_mask:0xf bank_mask:0xf bound_ctrl:1
	v_add_f32_dpp v72, v72, v72 row_ror:4 row_mask:0xf bank_mask:0xf bound_ctrl:1
	v_add_f32_dpp v64, v64, v64 row_ror:2 row_mask:0xf bank_mask:0xf bound_ctrl:1
	v_add_f32_dpp v68, v68, v68 row_ror:2 row_mask:0xf bank_mask:0xf bound_ctrl:1
	v_add_f32_dpp v72, v72, v72 row_ror:2 row_mask:0xf bank_mask:0xf bound_ctrl:1
	v_mov_b32_dpp v66, v64 row_ror:1 row_mask:0xf bank_mask:0xf
	v_mov_b32_dpp v70, v68 row_ror:1 row_mask:0xf bank_mask:0xf
	v_mov_b32_dpp v74, v72 row_ror:1 row_mask:0xf bank_mask:0xf
	v_cvt_f32_i32_e32 v186, v186
	v_cvt_f32_i32_e32 v187, v187
	v_cvt_f32_i32_e32 v188, v188
	v_add_f32_e32 v64, v64, v66
	v_add_f32_e32 v68, v68, v70
	v_add_f32_e32 v72, v72, v74
	v_fma_f32 v186, -v8, v186, v64
	v_fma_f32 v187, -v8, v187, v68
	v_fma_f32 v188, -v8, v188, v72
	v_mul_f32_e32 v186, 0x3fb8aa3b, v186
	v_mul_f32_e32 v187, 0x3fb8aa3b, v187
	v_mul_f32_e32 v188, 0x3fb8aa3b, v188
	s_and_b64 exec, s[98:99], s[10:11]
	ds_write_b32 v10, v186 offset:192
	ds_write_b32 v10, v187 offset:208
	ds_write_b32 v10, v188 offset:224
	s_mov_b64 exec, s[98:99]
	s_waitcnt vmcnt(15)
	v_mul_f32_e32 v77, v1, v77
	v_mul_f32_e32 v81, v1, v81
	v_mul_f32_e32 v85, v1, v85
	v_mul_f32_e32 v79, v3, v79
	v_mul_f32_e32 v83, v3, v83
	v_mul_f32_e32 v87, v3, v87
	v_fmac_f32_e32 v77, v0, v76
	v_fmac_f32_e32 v81, v0, v80
	v_fmac_f32_e32 v85, v0, v84
	v_fmac_f32_e32 v79, v2, v78
	v_fmac_f32_e32 v83, v2, v82
	v_fmac_f32_e32 v87, v2, v86
	v_add_f32_e32 v76, v77, v79
	v_add_f32_e32 v80, v81, v83
	v_add_f32_e32 v84, v85, v87
	v_mov_b32_e32 v78, 0
	v_mov_b32_e32 v82, 0
	v_mov_b32_e32 v86, 0
	v_add_f32_dpp v76, v76, v76 row_ror:8 row_mask:0xf bank_mask:0xf bound_ctrl:1
	v_add_f32_dpp v80, v80, v80 row_ror:8 row_mask:0xf bank_mask:0xf bound_ctrl:1
	v_add_f32_dpp v84, v84, v84 row_ror:8 row_mask:0xf bank_mask:0xf bound_ctrl:1
	v_add_f32_dpp v76, v76, v76 row_ror:4 row_mask:0xf bank_mask:0xf bound_ctrl:1
	v_add_f32_dpp v80, v80, v80 row_ror:4 row_mask:0xf bank_mask:0xf bound_ctrl:1
	v_add_f32_dpp v84, v84, v84 row_ror:4 row_mask:0xf bank_mask:0xf bound_ctrl:1
	v_add_f32_dpp v76, v76, v76 row_ror:2 row_mask:0xf bank_mask:0xf bound_ctrl:1
	v_add_f32_dpp v80, v80, v80 row_ror:2 row_mask:0xf bank_mask:0xf bound_ctrl:1
	v_add_f32_dpp v84, v84, v84 row_ror:2 row_mask:0xf bank_mask:0xf bound_ctrl:1
	v_mov_b32_dpp v78, v76 row_ror:1 row_mask:0xf bank_mask:0xf
	v_mov_b32_dpp v82, v80 row_ror:1 row_mask:0xf bank_mask:0xf
	v_mov_b32_dpp v86, v84 row_ror:1 row_mask:0xf bank_mask:0xf
	v_cvt_f32_i32_e32 v194, v194
	v_cvt_f32_i32_e32 v195, v195
	v_cvt_f32_i32_e32 v196, v196
	v_add_f32_e32 v76, v76, v78
	v_add_f32_e32 v80, v80, v82
	v_add_f32_e32 v84, v84, v86
	v_fma_f32 v194, -v8, v194, v76
	v_fma_f32 v195, -v8, v195, v80
	v_fma_f32 v196, -v8, v196, v84
	v_mul_f32_e32 v194, 0x3fb8aa3b, v194
	v_mul_f32_e32 v195, 0x3fb8aa3b, v195
	v_mul_f32_e32 v196, 0x3fb8aa3b, v196
	s_and_b64 exec, s[98:99], s[10:11]
	ds_write_b32 v10, v194 offset:240
	ds_write_b32 v10, v195 offset:256
	ds_write_b32 v10, v196 offset:272
	s_mov_b64 exec, s[98:99]
	s_waitcnt vmcnt(12)
	v_mul_f32_e32 v89, v1, v89
	v_mul_f32_e32 v93, v1, v93
	v_mul_f32_e32 v97, v1, v97
	v_mul_f32_e32 v91, v3, v91
	v_mul_f32_e32 v95, v3, v95
	v_mul_f32_e32 v99, v3, v99
	v_fmac_f32_e32 v89, v0, v88
	v_fmac_f32_e32 v93, v0, v92
	v_fmac_f32_e32 v97, v0, v96
	v_fmac_f32_e32 v91, v2, v90
	v_fmac_f32_e32 v95, v2, v94
	v_fmac_f32_e32 v99, v2, v98
	v_add_f32_e32 v88, v89, v91
	v_add_f32_e32 v92, v93, v95
	v_add_f32_e32 v96, v97, v99
	v_mov_b32_e32 v90, 0
	v_mov_b32_e32 v94, 0
	v_mov_b32_e32 v98, 0
	v_add_f32_dpp v88, v88, v88 row_ror:8 row_mask:0xf bank_mask:0xf bound_ctrl:1
	v_add_f32_dpp v92, v92, v92 row_ror:8 row_mask:0xf bank_mask:0xf bound_ctrl:1
	v_add_f32_dpp v96, v96, v96 row_ror:8 row_mask:0xf bank_mask:0xf bound_ctrl:1
	v_add_f32_dpp v88, v88, v88 row_ror:4 row_mask:0xf bank_mask:0xf bound_ctrl:1
	v_add_f32_dpp v92, v92, v92 row_ror:4 row_mask:0xf bank_mask:0xf bound_ctrl:1
	v_add_f32_dpp v96, v96, v96 row_ror:4 row_mask:0xf bank_mask:0xf bound_ctrl:1
	v_add_f32_dpp v88, v88, v88 row_ror:2 row_mask:0xf bank_mask:0xf bound_ctrl:1
	v_add_f32_dpp v92, v92, v92 row_ror:2 row_mask:0xf bank_mask:0xf bound_ctrl:1
	v_add_f32_dpp v96, v96, v96 row_ror:2 row_mask:0xf bank_mask:0xf bound_ctrl:1
	v_mov_b32_dpp v90, v88 row_ror:1 row_mask:0xf bank_mask:0xf
	v_mov_b32_dpp v94, v92 row_ror:1 row_mask:0xf bank_mask:0xf
	v_mov_b32_dpp v98, v96 row_ror:1 row_mask:0xf bank_mask:0xf
	v_cvt_f32_i32_e32 v197, v197
	v_cvt_f32_i32_e32 v198, v198
	v_cvt_f32_i32_e32 v199, v199
	v_add_f32_e32 v88, v88, v90
	v_add_f32_e32 v92, v92, v94
	v_add_f32_e32 v96, v96, v98
	v_fma_f32 v197, -v8, v197, v88
	v_fma_f32 v198, -v8, v198, v92
	v_fma_f32 v199, -v8, v199, v96
	v_mul_f32_e32 v197, 0x3fb8aa3b, v197
	v_mul_f32_e32 v198, 0x3fb8aa3b, v198
	v_mul_f32_e32 v199, 0x3fb8aa3b, v199
	s_and_b64 exec, s[98:99], s[10:11]
	ds_write_b32 v10, v197 offset:288
	ds_write_b32 v10, v198 offset:304
	ds_write_b32 v10, v199 offset:320
	s_mov_b64 exec, s[98:99]
	s_waitcnt vmcnt(9)
	v_mul_f32_e32 v17, v1, v17
	v_mul_f32_e32 v21, v1, v21
	v_mul_f32_e32 v25, v1, v25
	v_mul_f32_e32 v19, v3, v19
	v_mul_f32_e32 v23, v3, v23
	v_mul_f32_e32 v27, v3, v27
	v_fmac_f32_e32 v17, v0, v16
	v_fmac_f32_e32 v21, v0, v20
	v_fmac_f32_e32 v25, v0, v24
	v_fmac_f32_e32 v19, v2, v18
	v_fmac_f32_e32 v23, v2, v22
	v_fmac_f32_e32 v27, v2, v26
	v_add_f32_e32 v16, v17, v19
	v_add_f32_e32 v20, v21, v23
	v_add_f32_e32 v24, v25, v27
	v_mov_b32_e32 v18, 0
	v_mov_b32_e32 v22, 0
	v_mov_b32_e32 v26, 0
	v_add_f32_dpp v16, v16, v16 row_ror:8 row_mask:0xf bank_mask:0xf bound_ctrl:1
	v_add_f32_dpp v20, v20, v20 row_ror:8 row_mask:0xf bank_mask:0xf bound_ctrl:1
	v_add_f32_dpp v24, v24, v24 row_ror:8 row_mask:0xf bank_mask:0xf bound_ctrl:1
	v_add_f32_dpp v16, v16, v16 row_ror:4 row_mask:0xf bank_mask:0xf bound_ctrl:1
	v_add_f32_dpp v20, v20, v20 row_ror:4 row_mask:0xf bank_mask:0xf bound_ctrl:1
	v_add_f32_dpp v24, v24, v24 row_ror:4 row_mask:0xf bank_mask:0xf bound_ctrl:1
	v_add_f32_dpp v16, v16, v16 row_ror:2 row_mask:0xf bank_mask:0xf bound_ctrl:1
	v_add_f32_dpp v20, v20, v20 row_ror:2 row_mask:0xf bank_mask:0xf bound_ctrl:1
	v_add_f32_dpp v24, v24, v24 row_ror:2 row_mask:0xf bank_mask:0xf bound_ctrl:1
	v_mov_b32_dpp v18, v16 row_ror:1 row_mask:0xf bank_mask:0xf
	v_mov_b32_dpp v22, v20 row_ror:1 row_mask:0xf bank_mask:0xf
	v_mov_b32_dpp v26, v24 row_ror:1 row_mask:0xf bank_mask:0xf
	v_cvt_f32_i32_e32 v200, v200
	v_cvt_f32_i32_e32 v201, v201
	v_cvt_f32_i32_e32 v202, v202
	v_add_f32_e32 v16, v16, v18
	v_add_f32_e32 v20, v20, v22
	v_add_f32_e32 v24, v24, v26
	v_fma_f32 v200, -v8, v200, v16
	v_fma_f32 v201, -v8, v201, v20
	v_fma_f32 v202, -v8, v202, v24
	v_mul_f32_e32 v200, 0x3fb8aa3b, v200
	v_mul_f32_e32 v201, 0x3fb8aa3b, v201
	v_mul_f32_e32 v202, 0x3fb8aa3b, v202
	s_and_b64 exec, s[98:99], s[10:11]
	ds_write_b32 v10, v200 offset:336
	ds_write_b32 v10, v201 offset:352
	ds_write_b32 v10, v202 offset:368
	s_mov_b64 exec, s[98:99]
	s_waitcnt vmcnt(6)
	v_mul_f32_e32 v29, v1, v29
	v_mul_f32_e32 v33, v1, v33
	v_mul_f32_e32 v37, v1, v37
	v_mul_f32_e32 v31, v3, v31
	v_mul_f32_e32 v35, v3, v35
	v_mul_f32_e32 v39, v3, v39
	v_fmac_f32_e32 v29, v0, v28
	v_fmac_f32_e32 v33, v0, v32
	v_fmac_f32_e32 v37, v0, v36
	v_fmac_f32_e32 v31, v2, v30
	v_fmac_f32_e32 v35, v2, v34
	v_fmac_f32_e32 v39, v2, v38
	v_add_f32_e32 v28, v29, v31
	v_add_f32_e32 v32, v33, v35
	v_add_f32_e32 v36, v37, v39
	v_mov_b32_e32 v30, 0
	v_mov_b32_e32 v34, 0
	v_mov_b32_e32 v38, 0
	v_add_f32_dpp v28, v28, v28 row_ror:8 row_mask:0xf bank_mask:0xf bound_ctrl:1
	v_add_f32_dpp v32, v32, v32 row_ror:8 row_mask:0xf bank_mask:0xf bound_ctrl:1
	v_add_f32_dpp v36, v36, v36 row_ror:8 row_mask:0xf bank_mask:0xf bound_ctrl:1
	v_add_f32_dpp v28, v28, v28 row_ror:4 row_mask:0xf bank_mask:0xf bound_ctrl:1
	v_add_f32_dpp v32, v32, v32 row_ror:4 row_mask:0xf bank_mask:0xf bound_ctrl:1
	v_add_f32_dpp v36, v36, v36 row_ror:4 row_mask:0xf bank_mask:0xf bound_ctrl:1
	v_add_f32_dpp v28, v28, v28 row_ror:2 row_mask:0xf bank_mask:0xf bound_ctrl:1
	v_add_f32_dpp v32, v32, v32 row_ror:2 row_mask:0xf bank_mask:0xf bound_ctrl:1
	v_add_f32_dpp v36, v36, v36 row_ror:2 row_mask:0xf bank_mask:0xf bound_ctrl:1
	v_mov_b32_dpp v30, v28 row_ror:1 row_mask:0xf bank_mask:0xf
	v_mov_b32_dpp v34, v32 row_ror:1 row_mask:0xf bank_mask:0xf
	v_mov_b32_dpp v38, v36 row_ror:1 row_mask:0xf bank_mask:0xf
	v_cvt_f32_i32_e32 v203, v203
	v_cvt_f32_i32_e32 v204, v204
	v_cvt_f32_i32_e32 v205, v205
	v_add_f32_e32 v28, v28, v30
	v_add_f32_e32 v32, v32, v34
	v_add_f32_e32 v36, v36, v38
	v_fma_f32 v203, -v8, v203, v28
	v_fma_f32 v204, -v8, v204, v32
	v_fma_f32 v205, -v8, v205, v36
	v_mul_f32_e32 v203, 0x3fb8aa3b, v203
	v_mul_f32_e32 v204, 0x3fb8aa3b, v204
	v_mul_f32_e32 v205, 0x3fb8aa3b, v205
	s_and_b64 exec, s[98:99], s[10:11]
	ds_write_b32 v10, v203 offset:384
	ds_write_b32 v10, v204 offset:400
	ds_write_b32 v10, v205 offset:416
	s_mov_b64 exec, s[98:99]
	s_waitcnt vmcnt(3)
	v_mul_f32_e32 v41, v1, v41
	v_mul_f32_e32 v45, v1, v45
	v_mul_f32_e32 v49, v1, v49
	v_mul_f32_e32 v43, v3, v43
	v_mul_f32_e32 v47, v3, v47
	v_mul_f32_e32 v51, v3, v51
	v_fmac_f32_e32 v41, v0, v40
	v_fmac_f32_e32 v45, v0, v44
	v_fmac_f32_e32 v49, v0, v48
	v_fmac_f32_e32 v43, v2, v42
	v_fmac_f32_e32 v47, v2, v46
	v_fmac_f32_e32 v51, v2, v50
	v_add_f32_e32 v40, v41, v43
	v_add_f32_e32 v44, v45, v47
	v_add_f32_e32 v48, v49, v51
	v_mov_b32_e32 v42, 0
	v_mov_b32_e32 v46, 0
	v_mov_b32_e32 v50, 0
	v_add_f32_dpp v40, v40, v40 row_ror:8 row_mask:0xf bank_mask:0xf bound_ctrl:1
	v_add_f32_dpp v44, v44, v44 row_ror:8 row_mask:0xf bank_mask:0xf bound_ctrl:1
	v_add_f32_dpp v48, v48, v48 row_ror:8 row_mask:0xf bank_mask:0xf bound_ctrl:1
	v_add_f32_dpp v40, v40, v40 row_ror:4 row_mask:0xf bank_mask:0xf bound_ctrl:1
	v_add_f32_dpp v44, v44, v44 row_ror:4 row_mask:0xf bank_mask:0xf bound_ctrl:1
	v_add_f32_dpp v48, v48, v48 row_ror:4 row_mask:0xf bank_mask:0xf bound_ctrl:1
	v_add_f32_dpp v40, v40, v40 row_ror:2 row_mask:0xf bank_mask:0xf bound_ctrl:1
	v_add_f32_dpp v44, v44, v44 row_ror:2 row_mask:0xf bank_mask:0xf bound_ctrl:1
	v_add_f32_dpp v48, v48, v48 row_ror:2 row_mask:0xf bank_mask:0xf bound_ctrl:1
	v_mov_b32_dpp v42, v40 row_ror:1 row_mask:0xf bank_mask:0xf
	v_mov_b32_dpp v46, v44 row_ror:1 row_mask:0xf bank_mask:0xf
	v_mov_b32_dpp v50, v48 row_ror:1 row_mask:0xf bank_mask:0xf
	v_cvt_f32_i32_e32 v206, v206
	v_cvt_f32_i32_e32 v207, v207
	v_cvt_f32_i32_e32 v208, v208
	v_add_f32_e32 v40, v40, v42
	v_add_f32_e32 v44, v44, v46
	v_add_f32_e32 v48, v48, v50
	v_fma_f32 v206, -v8, v206, v40
	v_fma_f32 v207, -v8, v207, v44
	v_fma_f32 v208, -v8, v208, v48
	v_mul_f32_e32 v206, 0x3fb8aa3b, v206
	v_mul_f32_e32 v207, 0x3fb8aa3b, v207
	v_mul_f32_e32 v208, 0x3fb8aa3b, v208
	s_and_b64 exec, s[98:99], s[10:11]
	ds_write_b32 v10, v206 offset:432
	ds_write_b32 v10, v207 offset:448
	ds_write_b32 v10, v208 offset:464
	s_mov_b64 exec, s[98:99]
	s_waitcnt vmcnt(0)
	v_mul_f32_e32 v53, v1, v53
	v_mul_f32_e32 v57, v1, v57
	v_mul_f32_e32 v61, v1, v61
	v_mul_f32_e32 v55, v3, v55
	v_mul_f32_e32 v59, v3, v59
	v_mul_f32_e32 v63, v3, v63
	v_fmac_f32_e32 v53, v0, v52
	v_fmac_f32_e32 v57, v0, v56
	v_fmac_f32_e32 v61, v0, v60
	v_fmac_f32_e32 v55, v2, v54
	v_fmac_f32_e32 v59, v2, v58
	v_fmac_f32_e32 v63, v2, v62
	v_add_f32_e32 v52, v53, v55
	v_add_f32_e32 v56, v57, v59
	v_add_f32_e32 v60, v61, v63
	v_mov_b32_e32 v54, 0
	v_mov_b32_e32 v58, 0
	v_mov_b32_e32 v62, 0
	v_add_f32_dpp v52, v52, v52 row_ror:8 row_mask:0xf bank_mask:0xf bound_ctrl:1
	v_add_f32_dpp v56, v56, v56 row_ror:8 row_mask:0xf bank_mask:0xf bound_ctrl:1
	v_add_f32_dpp v60, v60, v60 row_ror:8 row_mask:0xf bank_mask:0xf bound_ctrl:1
	v_add_f32_dpp v52, v52, v52 row_ror:4 row_mask:0xf bank_mask:0xf bound_ctrl:1
	v_add_f32_dpp v56, v56, v56 row_ror:4 row_mask:0xf bank_mask:0xf bound_ctrl:1
	v_add_f32_dpp v60, v60, v60 row_ror:4 row_mask:0xf bank_mask:0xf bound_ctrl:1
	v_add_f32_dpp v52, v52, v52 row_ror:2 row_mask:0xf bank_mask:0xf bound_ctrl:1
	v_add_f32_dpp v56, v56, v56 row_ror:2 row_mask:0xf bank_mask:0xf bound_ctrl:1
	v_add_f32_dpp v60, v60, v60 row_ror:2 row_mask:0xf bank_mask:0xf bound_ctrl:1
	v_mov_b32_dpp v54, v52 row_ror:1 row_mask:0xf bank_mask:0xf
	v_mov_b32_dpp v58, v56 row_ror:1 row_mask:0xf bank_mask:0xf
	v_mov_b32_dpp v62, v60 row_ror:1 row_mask:0xf bank_mask:0xf
	v_cvt_f32_i32_e32 v190, v190
	v_cvt_f32_i32_e32 v191, v191
	v_cvt_f32_i32_e32 v192, v192
	v_add_f32_e32 v52, v52, v54
	v_add_f32_e32 v56, v56, v58
	v_add_f32_e32 v60, v60, v62
	v_fma_f32 v190, -v8, v190, v52
	v_fma_f32 v191, -v8, v191, v56
	v_fma_f32 v192, -v8, v192, v60
	v_mul_f32_e32 v190, 0x3fb8aa3b, v190
	v_mul_f32_e32 v191, 0x3fb8aa3b, v191
	v_mul_f32_e32 v192, 0x3fb8aa3b, v192
	v_add_u32_e32 v12, -8, v9
	v_cmp_gt_u32_e32 vcc, s14, v12
	s_and_b64 s[12:13], s[10:11], vcc
	s_and_b64 exec, s[98:99], s[12:13]
	ds_write_b32 v10, v190 offset:480
	s_mov_b64 exec, s[98:99]
	v_add_u32_e32 v12, -4, v9
	v_cmp_gt_u32_e32 vcc, s14, v12
	s_and_b64 s[12:13], s[10:11], vcc
	s_and_b64 exec, s[98:99], s[12:13]
	ds_write_b32 v10, v191 offset:496
	s_mov_b64 exec, s[98:99]
	v_cmp_gt_u32_e32 vcc, s14, v9
	s_and_b64 s[12:13], s[10:11], vcc
	s_and_b64 exec, s[98:99], s[12:13]
	ds_write_b32 v10, v192 offset:512
	s_mov_b64 exec, s[98:99]
	s_mov_b64 s[0:1], s[98:99]
	s_branch .LBB0_309

	.amdhsa_kernel _Z3fwd4Args
		.amdhsa_group_segment_fixed_size 0
		.amdhsa_private_segment_fixed_size 0
		.amdhsa_kernarg_size 408
		.amdhsa_user_sgpr_count 2
		.amdhsa_user_sgpr_dispatch_ptr 0
		.amdhsa_user_sgpr_queue_ptr 0
		.amdhsa_user_sgpr_kernarg_segment_ptr 1
		.amdhsa_user_sgpr_dispatch_id 0
		.amdhsa_user_sgpr_kernarg_preload_length 0
		.amdhsa_user_sgpr_kernarg_preload_offset 0
		.amdhsa_user_sgpr_private_segment_size 0
		.amdhsa_uses_dynamic_stack 0
		.amdhsa_enable_private_segment 0
		.amdhsa_system_sgpr_workgroup_id_x 1
		.amdhsa_system_sgpr_workgroup_id_y 0
		.amdhsa_system_sgpr_workgroup_id_z 0
		.amdhsa_system_sgpr_workgroup_info 0
		.amdhsa_system_vgpr_workitem_id 2
		.amdhsa_next_free_vgpr 252
		.amdhsa_next_free_sgpr 100
		.amdhsa_accum_offset 252
		.amdhsa_reserve_vcc 1
		.amdhsa_float_round_mode_32 0
		.amdhsa_float_round_mode_16_64 0
		.amdhsa_float_denorm_mode_32 3
		.amdhsa_float_denorm_mode_16_64 3
		.amdhsa_dx10_clamp 1
		.amdhsa_ieee_mode 1
		.amdhsa_fp16_overflow 0
		.amdhsa_tg_split 0
		.amdhsa_exception_fp_ieee_invalid_op 0
		.amdhsa_exception_fp_denorm_src 0
		.amdhsa_exception_fp_ieee_div_zero 0
		.amdhsa_exception_fp_ieee_overflow 0
		.amdhsa_exception_fp_ieee_underflow 0
		.amdhsa_exception_fp_ieee_inexact 0
		.amdhsa_exception_int_div_zero 0
	.end_amdhsa_kernel

amdhsa.kernels:
  - .agpr_count:     0
    .args:
      - .offset:         0
        .size:           152
        .value_kind:     by_value
      - .offset:         152
        .size:           4
        .value_kind:     hidden_block_count_x
      - .offset:         156
        .size:           4
        .value_kind:     hidden_block_count_y
      - .offset:         160
        .size:           4
        .value_kind:     hidden_block_count_z
      - .offset:         164
        .size:           2
        .value_kind:     hidden_group_size_x
      - .offset:         166
        .size:           2
        .value_kind:     hidden_group_size_y
      - .offset:         168
        .size:           2
        .value_kind:     hidden_group_size_z
      - .offset:         170
        .size:           2
        .value_kind:     hidden_remainder_x
      - .offset:         172
        .size:           2
        .value_kind:     hidden_remainder_y
      - .offset:         174
        .size:           2
        .value_kind:     hidden_remainder_z
      - .offset:         192
        .size:           8
        .value_kind:     hidden_global_offset_x
      - .offset:         200
        .size:           8
        .value_kind:     hidden_global_offset_y
      - .offset:         208
        .size:           8
        .value_kind:     hidden_global_offset_z
      - .offset:         216
        .size:           2
        .value_kind:     hidden_grid_dims
      - .offset:         240
        .size:           8
        .value_kind:     hidden_multigrid_sync_arg
      - .offset:         272
        .size:           4
        .value_kind:     hidden_dynamic_lds_size
    .group_segment_fixed_size: 0
    .kernarg_segment_align: 8
    .kernarg_segment_size: 408
    .language:       OpenCL C
    .language_version:
      - 2
      - 0
    .max_flat_workgroup_size: 512
    .name:           _Z3fwd4Args
    .private_segment_fixed_size: 0
    .sgpr_count:     106
    .sgpr_spill_count: 52
    .symbol:         _Z3fwd4Args.kd
    .uniform_work_group_size: 1
    .uses_dynamic_stack: false
    .vgpr_count:     252
    .vgpr_spill_count: 0
    .wavefront_size: 64
